# INB/OUTA/OUTB K-loops: address VALU moved between the M0 write and its LDS-DMA load (24 s_nop removed) and INB's duplicated loop-top lgkmcnt(0) removed; on top of v98
# baseline (speedup 1.0000x reference)
; #define PG8_STAGE(bufoff, gbase, voff) do { _Pragma("unroll") for (int _i = 0; _i < 2; ++_i) \
;         __builtin_amdgcn_global_load_lds((const unsigned*)((const char*)(gbase) + (voff)[_i]), (PG8_LAS unsigned*)(lds + (bufoff) + ldsw + _i * 8192), 16, 0, 0); } while (0)
; #define PG8_LDA(dst, b, h) do { _Pragma("unroll") for (int m = 0; m < 4; ++m) _Pragma("unroll") for (int k = 0; k < 2; ++k) dst[m][k] = *(const PG8_LAS bf16x8*)(lds + PG8_SA(b, h) + aoff + m * 2048 + k * 1024); } while (0)
; #define PG8_LDB(dst, b, h) do { _Pragma("unroll") for (int n = 0; n < 2; ++n) _Pragma("unroll") for (int k = 0; k < 2; ++k) dst[n][k] = *(const PG8_LAS bf16x8*)(lds + PG8_SB(b, h) + boff + n * 2048 + k * 1024); } while (0)
; #define PG8_WAIT_V(n) asm volatile("s_waitcnt vmcnt(" #n ")" ::: "memory")
; #define PG8_WAIT_L(n) asm volatile("s_waitcnt lgkmcnt(" #n ")" ::: "memory")
; #define PG8_BAR __builtin_amdgcn_s_barrier()
; #define PG8_SCHED __builtin_amdgcn_sched_barrier(0)
;     ...
;         const bool has_next = S.next(ui + 1, nxt);
;         const char* nA = has_next ? (const char*)g.A + (size_t)nxt.pm * tstep : cA; const char* nB = has_next ? (const char*)g.Bt + (size_t)nxt.pn * tstep : cB;
;         for (int t = 0; t < nt; t += 2) {
;             const bool last = (t == nt - 2);
;             const char* a1 = cA + (size_t)(t + 1) * kstep;
;             const char* a2 = last ? nA : cA + (size_t)(t + 2) * kstep; const char* b2 = last ? nB : cB + (size_t)(t + 2) * kstep;
;             const char* a3 = a2 + kstep; const char* b3 = b2 + kstep;
;             PG8_LDB(B0, 0, 0); PG8_LDB(B1, 0, 1); PG8_SCHED; PG8_LDA(At, 0, 0); PG8_STAGE(PG8_SA(1, 1), a1 + hstep, voffA);
;             PG8_WAIT_V(8); PG8_WAIT_L(0); PG8_BAR; PG8_MMA(0, 0, At, B0); PG8_MMA(0, 1, At, B1); PG8_BAR; PG8_SCHED;
;             PG8_LDA(At, 0, 1); PG8_STAGE(PG8_SB(0, 0), b2, voffB); PG8_STAGE(PG8_SB(0, 1), b2 + hstepB, voffB); PG8_STAGE(PG8_SA(0, 0), a2, voffA);
;             PG8_WAIT_V(8); PG8_WAIT_L(0); PG8_BAR; PG8_MMA(1, 0, At, B0); PG8_MMA(1, 1, At, B1); PG8_BAR; PG8_SCHED;
;             PG8_LDB(B0, 1, 0); PG8_LDB(B1, 1, 1); PG8_SCHED; PG8_LDA(At, 1, 0); PG8_STAGE(PG8_SA(0, 1), a2 + hstep, voffA);
.LBB0_434:
	v_add_u32_e32 v140, s49, v199
	s_waitcnt lgkmcnt(0)
	v_add_u32_e32 v156, s50, v199
	ds_read_b128 v[128:131], v140
	ds_read_b128 v[132:135], v140 offset:1024
	ds_read_b128 v[136:139], v140 offset:2048
	ds_read_b128 v[140:143], v140 offset:3072
	ds_read_b128 v[144:147], v156
	ds_read_b128 v[148:151], v156 offset:1024
	ds_read_b128 v[152:155], v156 offset:2048
	ds_read_b128 v[156:159], v156 offset:3072
	s_add_u32 s22, s24, 0xfffc0080
	s_addc_u32 s23, s25, -1
	s_cmp_eq_u32 s54, 12
	s_cselect_b32 s27, s2, s23
	s_cselect_b32 s26, s15, s22
	s_cselect_b32 s23, s13, s53
	s_cselect_b32 s22, s21, s52
	v_lshl_add_u64 v[196:197], s[24:25], 0, v[184:185]
	s_add_i32 m0, s29, 0xc000
	ds_read_b128 v[160:163], v201
	ds_read_b128 v[164:167], v201 offset:1024
	ds_read_b128 v[168:171], v201 offset:2048
	ds_read_b128 v[172:175], v201 offset:3072
	ds_read_b128 v[192:195], v201 offset:4096
	ds_read_b128 v[202:205], v201 offset:5120
	ds_read_b128 v[206:209], v201 offset:6144
	ds_read_b128 v[210:213], v201 offset:7168
	global_load_lds_dwordx4 v[196:197], off
	s_add_i32 m0, s29, 0xe000
	v_lshl_add_u64 v[196:197], s[24:25], 0, v[186:187]
	global_load_lds_dwordx4 v[196:197], off
	s_waitcnt vmcnt(8)
	s_waitcnt lgkmcnt(0)
	s_barrier
	v_mfma_f32_16x16x32_bf16 v[112:115], v[128:131], v[160:163], v[112:115]
	v_mfma_f32_16x16x32_bf16 v[116:119], v[136:139], v[160:163], v[116:119]
	v_mfma_f32_16x16x32_bf16 v[108:111], v[128:131], v[168:171], v[108:111]
	v_mfma_f32_16x16x32_bf16 v[104:107], v[136:139], v[168:171], v[104:107]
	v_mfma_f32_16x16x32_bf16 v[92:95], v[128:131], v[192:195], v[92:95]
	v_mfma_f32_16x16x32_bf16 v[88:91], v[136:139], v[192:195], v[88:91]
	v_mfma_f32_16x16x32_bf16 v[76:79], v[128:131], v[206:209], v[76:79]
	v_mfma_f32_16x16x32_bf16 v[72:75], v[136:139], v[206:209], v[72:75]
	v_mfma_f32_16x16x32_bf16 v[112:115], v[132:135], v[164:167], v[112:115]
	v_mfma_f32_16x16x32_bf16 v[116:119], v[140:143], v[164:167], v[116:119]
	v_mfma_f32_16x16x32_bf16 v[108:111], v[132:135], v[172:175], v[108:111]
	v_mfma_f32_16x16x32_bf16 v[104:107], v[140:143], v[172:175], v[104:107]
	v_mfma_f32_16x16x32_bf16 v[92:95], v[132:135], v[202:205], v[92:95]
	v_mfma_f32_16x16x32_bf16 v[88:91], v[140:143], v[202:205], v[88:91]
	v_mfma_f32_16x16x32_bf16 v[76:79], v[132:135], v[210:213], v[76:79]
	v_mfma_f32_16x16x32_bf16 v[72:75], v[140:143], v[210:213], v[72:75]
	v_mfma_f32_16x16x32_bf16 v[120:123], v[144:147], v[160:163], v[120:123]
	v_mfma_f32_16x16x32_bf16 v[124:127], v[152:155], v[160:163], v[124:127]
	v_mfma_f32_16x16x32_bf16 v[100:103], v[144:147], v[168:171], v[100:103]
	v_mfma_f32_16x16x32_bf16 v[96:99], v[152:155], v[168:171], v[96:99]
	v_mfma_f32_16x16x32_bf16 v[84:87], v[144:147], v[192:195], v[84:87]
	v_mfma_f32_16x16x32_bf16 v[80:83], v[152:155], v[192:195], v[80:83]
	v_mfma_f32_16x16x32_bf16 v[68:71], v[144:147], v[206:209], v[68:71]
	v_mfma_f32_16x16x32_bf16 v[64:67], v[152:155], v[206:209], v[64:67]
	v_mfma_f32_16x16x32_bf16 v[120:123], v[148:151], v[164:167], v[120:123]
	v_mfma_f32_16x16x32_bf16 v[124:127], v[156:159], v[164:167], v[124:127]
	v_mfma_f32_16x16x32_bf16 v[100:103], v[148:151], v[172:175], v[100:103]
	v_mfma_f32_16x16x32_bf16 v[96:99], v[156:159], v[172:175], v[96:99]
	v_mfma_f32_16x16x32_bf16 v[84:87], v[148:151], v[202:205], v[84:87]
	v_mfma_f32_16x16x32_bf16 v[80:83], v[156:159], v[202:205], v[80:83]
	v_mfma_f32_16x16x32_bf16 v[68:71], v[148:151], v[210:213], v[68:71]
	v_mfma_f32_16x16x32_bf16 v[64:67], v[156:159], v[210:213], v[64:67]
	s_barrier
	s_add_i32 s55, s49, s28
	v_lshl_add_u64 v[196:197], s[22:23], 0, v[178:179]
	s_mov_b32 m0, s55
	ds_read_b128 v[160:163], v201 offset:16384
	ds_read_b128 v[164:167], v201 offset:17408
	ds_read_b128 v[168:171], v201 offset:18432
	ds_read_b128 v[172:175], v201 offset:19456
	ds_read_b128 v[192:195], v201 offset:20480
	ds_read_b128 v[202:205], v201 offset:21504
	ds_read_b128 v[206:209], v201 offset:22528
	ds_read_b128 v[210:213], v201 offset:23552
	global_load_lds_dwordx4 v[196:197], off
	s_add_i32 m0, s55, 0x2000
	s_add_u32 s56, s22, 0x40000
	v_lshl_add_u64 v[214:215], s[22:23], 0, v[176:177]
	s_addc_u32 s57, s23, 0
	s_add_i32 s55, s50, s28
	global_load_lds_dwordx4 v[214:215], off
	v_lshl_add_u64 v[216:217], s[56:57], 0, v[178:179]
	s_mov_b32 m0, s55
	v_lshl_add_u64 v[218:219], s[26:27], 0, v[176:177]
	global_load_lds_dwordx4 v[216:217], off
	s_add_i32 m0, s55, 0x2000
	v_lshl_add_u64 v[216:217], s[56:57], 0, v[176:177]
	global_load_lds_dwordx4 v[216:217], off
	s_mov_b32 m0, s29
	v_lshl_add_u64 v[216:217], s[26:27], 0, v[178:179]
	global_load_lds_dwordx4 v[216:217], off
	s_mov_b32 m0, s33
	s_nop 0
	global_load_lds_dwordx4 v[218:219], off
	s_waitcnt vmcnt(8)
	s_waitcnt lgkmcnt(0)
	s_barrier
; #define PG8_STAGE(bufoff, gbase, voff) do { _Pragma("unroll") for (int _i = 0; _i < 2; ++_i) \
;         __builtin_amdgcn_global_load_lds((const unsigned*)((const char*)(gbase) + (voff)[_i]), (PG8_LAS unsigned*)(lds + (bufoff) + ldsw + _i * 8192), 16, 0, 0); } while (0)
; #define PG8_LDA(dst, b, h) do { _Pragma("unroll") for (int m = 0; m < 4; ++m) _Pragma("unroll") for (int k = 0; k < 2; ++k) dst[m][k] = *(const PG8_LAS bf16x8*)(lds + PG8_SA(b, h) + aoff + m * 2048 + k * 1024); } while (0)
; #define PG8_WAIT_V(n) asm volatile("s_waitcnt vmcnt(" #n ")" ::: "memory")
; #define PG8_WAIT_L(n) asm volatile("s_waitcnt lgkmcnt(" #n ")" ::: "memory")
; #define PG8_BAR __builtin_amdgcn_s_barrier()
; #define PG8_SCHED __builtin_amdgcn_sched_barrier(0)
;     ...
;             PG8_WAIT_V(8); PG8_WAIT_L(0); PG8_BAR; PG8_MMA(0, 0, At, B0); PG8_MMA(0, 1, At, B1); PG8_BAR; PG8_SCHED;
;             PG8_LDA(At, 1, 1); PG8_STAGE(PG8_SB(1, 0), b3, voffB); PG8_STAGE(PG8_SB(1, 1), b3 + hstepB, voffB); PG8_STAGE(PG8_SA(1, 0), a3, voffA);
;             PG8_WAIT_V(8); PG8_WAIT_L(0); PG8_BAR; PG8_MMA(1, 0, At, B0); PG8_MMA(1, 1, At, B1); PG8_BAR; PG8_SCHED;
	v_mfma_f32_16x16x32_bf16 v[60:63], v[128:131], v[160:163], v[60:63]
	v_mfma_f32_16x16x32_bf16 v[52:55], v[136:139], v[160:163], v[52:55]
	v_mfma_f32_16x16x32_bf16 v[44:47], v[128:131], v[168:171], v[44:47]
	v_mfma_f32_16x16x32_bf16 v[36:39], v[136:139], v[168:171], v[36:39]
	v_mfma_f32_16x16x32_bf16 v[28:31], v[128:131], v[192:195], v[28:31]
	v_mfma_f32_16x16x32_bf16 v[20:23], v[136:139], v[192:195], v[20:23]
	v_mfma_f32_16x16x32_bf16 v[8:11], v[128:131], v[206:209], v[8:11]
	v_mfma_f32_16x16x32_bf16 v[0:3], v[136:139], v[206:209], v[0:3]
	v_mfma_f32_16x16x32_bf16 v[60:63], v[132:135], v[164:167], v[60:63]
	v_mfma_f32_16x16x32_bf16 v[52:55], v[140:143], v[164:167], v[52:55]
	v_mfma_f32_16x16x32_bf16 v[44:47], v[132:135], v[172:175], v[44:47]
	v_mfma_f32_16x16x32_bf16 v[36:39], v[140:143], v[172:175], v[36:39]
	v_mfma_f32_16x16x32_bf16 v[28:31], v[132:135], v[202:205], v[28:31]
	v_mfma_f32_16x16x32_bf16 v[20:23], v[140:143], v[202:205], v[20:23]
	v_mfma_f32_16x16x32_bf16 v[8:11], v[132:135], v[210:213], v[8:11]
	v_mfma_f32_16x16x32_bf16 v[0:3], v[140:143], v[210:213], v[0:3]
	v_mfma_f32_16x16x32_bf16 v[56:59], v[144:147], v[160:163], v[56:59]
	v_mfma_f32_16x16x32_bf16 v[48:51], v[152:155], v[160:163], v[48:51]
	v_mfma_f32_16x16x32_bf16 v[40:43], v[144:147], v[168:171], v[40:43]
	v_mfma_f32_16x16x32_bf16 v[32:35], v[152:155], v[168:171], v[32:35]
	v_mfma_f32_16x16x32_bf16 v[24:27], v[144:147], v[192:195], v[24:27]
	v_mfma_f32_16x16x32_bf16 v[16:19], v[152:155], v[192:195], v[16:19]
	v_mfma_f32_16x16x32_bf16 v[4:7], v[144:147], v[206:209], v[4:7]
	v_mfma_f32_16x16x32_bf16 v[12:15], v[152:155], v[206:209], v[12:15]
	v_mfma_f32_16x16x32_bf16 v[56:59], v[148:151], v[164:167], v[56:59]
	v_mfma_f32_16x16x32_bf16 v[48:51], v[156:159], v[164:167], v[48:51]
	v_mfma_f32_16x16x32_bf16 v[40:43], v[148:151], v[172:175], v[40:43]
	v_mfma_f32_16x16x32_bf16 v[32:35], v[156:159], v[172:175], v[32:35]
	v_mfma_f32_16x16x32_bf16 v[24:27], v[148:151], v[202:205], v[24:27]
	v_mfma_f32_16x16x32_bf16 v[16:19], v[156:159], v[202:205], v[16:19]
	v_mfma_f32_16x16x32_bf16 v[4:7], v[148:151], v[210:213], v[4:7]
	v_mfma_f32_16x16x32_bf16 v[12:15], v[156:159], v[210:213], v[12:15]
	s_barrier
	s_add_i32 s55, 0, 0x18000
	s_add_i32 s56, 0, 0x1c000
	v_add_u32_e32 v140, s55, v199
	v_add_u32_e32 v156, s56, v199
	ds_read_b128 v[128:131], v140
	ds_read_b128 v[132:135], v140 offset:1024
	ds_read_b128 v[136:139], v140 offset:2048
	ds_read_b128 v[140:143], v140 offset:3072
	ds_read_b128 v[144:147], v156
	ds_read_b128 v[148:151], v156 offset:1024
	ds_read_b128 v[152:155], v156 offset:2048
	ds_read_b128 v[156:159], v156 offset:3072
	s_add_u32 s26, s26, 0x40000
	s_addc_u32 s27, s27, 0
	s_mov_b32 m0, s36
	v_lshl_add_u64 v[220:221], s[26:27], 0, v[178:179]
	ds_read_b128 v[160:163], v201 offset:32768
	ds_read_b128 v[164:167], v201 offset:33792
	ds_read_b128 v[168:171], v201 offset:34816
	ds_read_b128 v[172:175], v201 offset:35840
	ds_read_b128 v[192:195], v201 offset:36864
	ds_read_b128 v[202:205], v201 offset:37888
	ds_read_b128 v[206:209], v201 offset:38912
	ds_read_b128 v[210:213], v201 offset:39936
	global_load_lds_dwordx4 v[220:221], off
	s_mov_b32 m0, s37
	v_lshl_add_u64 v[220:221], s[26:27], 0, v[176:177]
	global_load_lds_dwordx4 v[220:221], off
	s_waitcnt vmcnt(8)
	s_waitcnt lgkmcnt(0)
	s_barrier
	v_mfma_f32_16x16x32_bf16 v[112:115], v[128:131], v[160:163], v[112:115]
	v_mfma_f32_16x16x32_bf16 v[116:119], v[136:139], v[160:163], v[116:119]
	v_mfma_f32_16x16x32_bf16 v[108:111], v[128:131], v[168:171], v[108:111]
	v_mfma_f32_16x16x32_bf16 v[104:107], v[136:139], v[168:171], v[104:107]
	v_mfma_f32_16x16x32_bf16 v[92:95], v[128:131], v[192:195], v[92:95]
	v_mfma_f32_16x16x32_bf16 v[88:91], v[136:139], v[192:195], v[88:91]
	v_mfma_f32_16x16x32_bf16 v[76:79], v[128:131], v[206:209], v[76:79]
	v_mfma_f32_16x16x32_bf16 v[72:75], v[136:139], v[206:209], v[72:75]
	v_mfma_f32_16x16x32_bf16 v[112:115], v[132:135], v[164:167], v[112:115]
	v_mfma_f32_16x16x32_bf16 v[116:119], v[140:143], v[164:167], v[116:119]
	v_mfma_f32_16x16x32_bf16 v[108:111], v[132:135], v[172:175], v[108:111]
	v_mfma_f32_16x16x32_bf16 v[104:107], v[140:143], v[172:175], v[104:107]
	v_mfma_f32_16x16x32_bf16 v[92:95], v[132:135], v[202:205], v[92:95]
	v_mfma_f32_16x16x32_bf16 v[88:91], v[140:143], v[202:205], v[88:91]
	v_mfma_f32_16x16x32_bf16 v[76:79], v[132:135], v[210:213], v[76:79]
	v_mfma_f32_16x16x32_bf16 v[72:75], v[140:143], v[210:213], v[72:75]
	v_mfma_f32_16x16x32_bf16 v[120:123], v[144:147], v[160:163], v[120:123]
	v_mfma_f32_16x16x32_bf16 v[124:127], v[152:155], v[160:163], v[124:127]
	v_mfma_f32_16x16x32_bf16 v[100:103], v[144:147], v[168:171], v[100:103]
	v_mfma_f32_16x16x32_bf16 v[96:99], v[152:155], v[168:171], v[96:99]
	v_mfma_f32_16x16x32_bf16 v[84:87], v[144:147], v[192:195], v[84:87]
	v_mfma_f32_16x16x32_bf16 v[80:83], v[152:155], v[192:195], v[80:83]
	v_mfma_f32_16x16x32_bf16 v[68:71], v[144:147], v[206:209], v[68:71]
	v_mfma_f32_16x16x32_bf16 v[64:67], v[152:155], v[206:209], v[64:67]
	v_mfma_f32_16x16x32_bf16 v[120:123], v[148:151], v[164:167], v[120:123]
	v_mfma_f32_16x16x32_bf16 v[124:127], v[156:159], v[164:167], v[124:127]
	v_mfma_f32_16x16x32_bf16 v[100:103], v[148:151], v[172:175], v[100:103]
	v_mfma_f32_16x16x32_bf16 v[96:99], v[156:159], v[172:175], v[96:99]
	v_mfma_f32_16x16x32_bf16 v[84:87], v[148:151], v[202:205], v[84:87]
	v_mfma_f32_16x16x32_bf16 v[80:83], v[156:159], v[202:205], v[80:83]
	v_mfma_f32_16x16x32_bf16 v[68:71], v[148:151], v[210:213], v[68:71]
	v_mfma_f32_16x16x32_bf16 v[64:67], v[156:159], v[210:213], v[64:67]
	s_barrier
; #define PG8_STAGE(bufoff, gbase, voff) do { _Pragma("unroll") for (int _i = 0; _i < 2; ++_i) \
;         __builtin_amdgcn_global_load_lds((const unsigned*)((const char*)(gbase) + (voff)[_i]), (PG8_LAS unsigned*)(lds + (bufoff) + ldsw + _i * 8192), 16, 0, 0); } while (0)
; #define PG8_LDA(dst, b, h) do { _Pragma("unroll") for (int m = 0; m < 4; ++m) _Pragma("unroll") for (int k = 0; k < 2; ++k) dst[m][k] = *(const PG8_LAS bf16x8*)(lds + PG8_SA(b, h) + aoff + m * 2048 + k * 1024); } while (0)
; #define PG8_WAIT_V(n) asm volatile("s_waitcnt vmcnt(" #n ")" ::: "memory")
; #define PG8_WAIT_L(n) asm volatile("s_waitcnt lgkmcnt(" #n ")" ::: "memory")
; #define PG8_BAR __builtin_amdgcn_s_barrier()
; #define PG8_SCHED __builtin_amdgcn_sched_barrier(0)
;     ...
;             PG8_LDA(At, 1, 1); PG8_STAGE(PG8_SB(1, 0), b3, voffB); PG8_STAGE(PG8_SB(1, 1), b3 + hstepB, voffB); PG8_STAGE(PG8_SA(1, 0), a3, voffA);
;             PG8_WAIT_V(8); PG8_WAIT_L(0); PG8_BAR; PG8_MMA(1, 0, At, B0); PG8_MMA(1, 1, At, B1); PG8_BAR; PG8_SCHED;
;         }
	s_add_i32 s26, s55, s28
	v_lshl_add_u64 v[196:197], v[196:197], 0, s[8:9]
	s_mov_b32 m0, s26
	ds_read_b128 v[160:163], v201 offset:49152
	ds_read_b128 v[164:167], v201 offset:50176
	ds_read_b128 v[168:171], v201 offset:51200
	ds_read_b128 v[172:175], v201 offset:52224
	ds_read_b128 v[192:195], v201 offset:53248
	ds_read_b128 v[202:205], v201 offset:54272
	ds_read_b128 v[206:209], v201 offset:55296
	ds_read_b128 v[210:213], v201 offset:56320
	global_load_lds_dwordx4 v[196:197], off
	s_add_i32 m0, s26, 0x2000
	s_add_u32 s22, s22, 0x40080
	v_lshl_add_u64 v[196:197], v[214:215], 0, s[8:9]
	s_addc_u32 s23, s23, 0
	s_add_i32 s26, s56, s28
	global_load_lds_dwordx4 v[196:197], off
	s_mov_b32 m0, s26
	v_lshl_add_u64 v[196:197], s[22:23], 0, v[178:179]
	global_load_lds_dwordx4 v[196:197], off
	s_add_i32 m0, s26, 0x2000
	v_lshl_add_u64 v[196:197], s[22:23], 0, v[176:177]
	global_load_lds_dwordx4 v[196:197], off
	s_mov_b32 m0, s41
	v_lshl_add_u64 v[196:197], v[216:217], 0, s[8:9]
	global_load_lds_dwordx4 v[196:197], off
	s_mov_b32 m0, s42
	v_lshl_add_u64 v[196:197], v[218:219], 0, s[8:9]
	global_load_lds_dwordx4 v[196:197], off
	s_waitcnt vmcnt(8)
	s_waitcnt lgkmcnt(0)
	s_barrier
	v_mfma_f32_16x16x32_bf16 v[60:63], v[128:131], v[160:163], v[60:63]
	v_mfma_f32_16x16x32_bf16 v[52:55], v[136:139], v[160:163], v[52:55]
	v_mfma_f32_16x16x32_bf16 v[44:47], v[128:131], v[168:171], v[44:47]
	v_mfma_f32_16x16x32_bf16 v[36:39], v[136:139], v[168:171], v[36:39]
	v_mfma_f32_16x16x32_bf16 v[28:31], v[128:131], v[192:195], v[28:31]
	v_mfma_f32_16x16x32_bf16 v[20:23], v[136:139], v[192:195], v[20:23]
	v_mfma_f32_16x16x32_bf16 v[8:11], v[128:131], v[206:209], v[8:11]
	v_mfma_f32_16x16x32_bf16 v[0:3], v[136:139], v[206:209], v[0:3]
	v_mfma_f32_16x16x32_bf16 v[60:63], v[132:135], v[164:167], v[60:63]
	v_mfma_f32_16x16x32_bf16 v[52:55], v[140:143], v[164:167], v[52:55]
	v_mfma_f32_16x16x32_bf16 v[44:47], v[132:135], v[172:175], v[44:47]
	v_mfma_f32_16x16x32_bf16 v[36:39], v[140:143], v[172:175], v[36:39]
	v_mfma_f32_16x16x32_bf16 v[28:31], v[132:135], v[202:205], v[28:31]
	v_mfma_f32_16x16x32_bf16 v[20:23], v[140:143], v[202:205], v[20:23]
	v_mfma_f32_16x16x32_bf16 v[8:11], v[132:135], v[210:213], v[8:11]
	v_mfma_f32_16x16x32_bf16 v[0:3], v[140:143], v[210:213], v[0:3]
	v_mfma_f32_16x16x32_bf16 v[56:59], v[144:147], v[160:163], v[56:59]
	v_mfma_f32_16x16x32_bf16 v[48:51], v[152:155], v[160:163], v[48:51]
	v_mfma_f32_16x16x32_bf16 v[40:43], v[144:147], v[168:171], v[40:43]
	v_mfma_f32_16x16x32_bf16 v[32:35], v[152:155], v[168:171], v[32:35]
	v_mfma_f32_16x16x32_bf16 v[24:27], v[144:147], v[192:195], v[24:27]
	v_mfma_f32_16x16x32_bf16 v[16:19], v[152:155], v[192:195], v[16:19]
	v_mfma_f32_16x16x32_bf16 v[4:7], v[144:147], v[206:209], v[4:7]
	v_mfma_f32_16x16x32_bf16 v[12:15], v[152:155], v[206:209], v[12:15]
	v_mfma_f32_16x16x32_bf16 v[56:59], v[148:151], v[164:167], v[56:59]
	v_mfma_f32_16x16x32_bf16 v[48:51], v[156:159], v[164:167], v[48:51]
	v_mfma_f32_16x16x32_bf16 v[40:43], v[148:151], v[172:175], v[40:43]
	v_mfma_f32_16x16x32_bf16 v[32:35], v[156:159], v[172:175], v[32:35]
	v_mfma_f32_16x16x32_bf16 v[24:27], v[148:151], v[202:205], v[24:27]
	v_mfma_f32_16x16x32_bf16 v[16:19], v[156:159], v[202:205], v[16:19]
	v_mfma_f32_16x16x32_bf16 v[4:7], v[148:151], v[210:213], v[4:7]
	v_mfma_f32_16x16x32_bf16 v[12:15], v[156:159], v[210:213], v[12:15]
	s_barrier
	s_add_i32 s54, s54, 2
	s_add_u32 s24, s24, 0x100
	s_addc_u32 s25, s25, 0
	s_add_u32 s52, s52, 0x100
	s_addc_u32 s53, s53, 0
	s_cmp_gt_u32 s54, 13
	s_cbranch_scc0 .LBB0_434
	s_and_b64 vcc, exec, s[10:11]
	s_cbranch_vccz .LBB0_437
	s_barrier

; #define PG8_STAGE(bufoff, gbase, voff) do { _Pragma("unroll") for (int _i = 0; _i < 2; ++_i) \
;         __builtin_amdgcn_global_load_lds((const unsigned*)((const char*)(gbase) + (voff)[_i]), (PG8_LAS unsigned*)(lds + (bufoff) + ldsw + _i * 8192), 16, 0, 0); } while (0)
; #define PG8_LDA(dst, b, h) do { _Pragma("unroll") for (int m = 0; m < 4; ++m) _Pragma("unroll") for (int k = 0; k < 2; ++k) dst[m][k] = *(const PG8_LAS bf16x8*)(lds + PG8_SA(b, h) + aoff + m * 2048 + k * 1024); } while (0)
; #define PG8_LDB(dst, b, h) do { _Pragma("unroll") for (int n = 0; n < 2; ++n) _Pragma("unroll") for (int k = 0; k < 2; ++k) dst[n][k] = *(const PG8_LAS bf16x8*)(lds + PG8_SB(b, h) + boff + n * 2048 + k * 1024); } while (0)
; #define PG8_SCHED __builtin_amdgcn_sched_barrier(0)
;     ...
;         const bool has_next = S.next(ui + 1, nxt);
;         const char* nA = has_next ? (const char*)g.A + (size_t)nxt.pm * tstep : cA; const char* nB = has_next ? (const char*)g.Bt + (size_t)nxt.pn * tstep : cB;
;         for (int t = 0; t < nt; t += 2) {
;             const bool last = (t == nt - 2);
;             const char* a1 = cA + (size_t)(t + 1) * kstep;
;             const char* a2 = last ? nA : cA + (size_t)(t + 2) * kstep; const char* b2 = last ? nB : cB + (size_t)(t + 2) * kstep;
;             const char* a3 = a2 + kstep; const char* b3 = b2 + kstep;
;             PG8_LDB(B0, 0, 0); PG8_LDB(B1, 0, 1); PG8_SCHED; PG8_LDA(At, 0, 0); PG8_STAGE(PG8_SA(1, 1), a1 + hstep, voffA);
.LBB0_532:
	s_waitcnt lgkmcnt(0)
	v_add_u32_e32 v124, s51, v197
	v_add_u32_e32 v156, s52, v197
	ds_read_b128 v[112:115], v124
	ds_read_b128 v[116:119], v124 offset:1024
	ds_read_b128 v[120:123], v124 offset:2048
	ds_read_b128 v[124:127], v124 offset:3072
	ds_read_b128 v[144:147], v156
	ds_read_b128 v[148:151], v156 offset:1024
	ds_read_b128 v[152:155], v156 offset:2048
	ds_read_b128 v[156:159], v156 offset:3072
	s_add_u32 s22, s24, 0xfffc0080
	s_addc_u32 s23, s25, -1
	s_cmp_eq_u32 s56, 12
	s_cselect_b32 s27, s2, s23
	s_cselect_b32 s26, s5, s22
	s_cselect_b32 s23, s7, s55
	s_cselect_b32 s22, s17, s39
	v_lshl_add_u64 v[218:219], s[24:25], 0, v[184:185]
	s_add_i32 m0, s29, 0xc000
	ds_read_b128 v[160:163], v200
	ds_read_b128 v[164:167], v200 offset:1024
	ds_read_b128 v[168:171], v200 offset:2048
	ds_read_b128 v[192:195], v200 offset:3072
	ds_read_b128 v[202:205], v200 offset:4096
	ds_read_b128 v[206:209], v200 offset:5120
	ds_read_b128 v[210:213], v200 offset:6144
	ds_read_b128 v[214:217], v200 offset:7168
	global_load_lds_dwordx4 v[218:219], off
	s_add_i32 m0, s29, 0xe000
	v_lshl_add_u64 v[218:219], s[24:25], 0, v[186:187]
	global_load_lds_dwordx4 v[218:219], off
	s_and_b32 s101, s101, 0xff
	s_cbranch_scc0 .Lpkb_w8a
	s_cmp_lt_i32 s56, 2
	s_cbranch_scc1 .Lpkb_w8a
	s_cmp_eq_u32 s101, 6
	s_cbranch_scc1 .Lpkb_s0
	s_cmp_eq_u32 s101, 5
	s_cbranch_scc1 .Lpkb_s1
	s_cmp_eq_u32 s101, 4
	s_cbranch_scc1 .Lpkb_s2
	s_cmp_eq_u32 s101, 3
	s_cbranch_scc1 .Lpkb_s3
	s_cmp_eq_u32 s101, 2
	s_cbranch_scc1 .Lpkb_s4
	global_store_dwordx4 v[254:255], v[248:251], off offset:64
	s_branch .Lpkb_w9a

; #define PG8_STAGE(bufoff, gbase, voff) do { _Pragma("unroll") for (int _i = 0; _i < 2; ++_i) \
;         __builtin_amdgcn_global_load_lds((const unsigned*)((const char*)(gbase) + (voff)[_i]), (PG8_LAS unsigned*)(lds + (bufoff) + ldsw + _i * 8192), 16, 0, 0); } while (0)
; #define PG8_LDA(dst, b, h) do { _Pragma("unroll") for (int m = 0; m < 4; ++m) _Pragma("unroll") for (int k = 0; k < 2; ++k) dst[m][k] = *(const PG8_LAS bf16x8*)(lds + PG8_SA(b, h) + aoff + m * 2048 + k * 1024); } while (0)
; #define PG8_WAIT_V(n) asm volatile("s_waitcnt vmcnt(" #n ")" ::: "memory")
; #define PG8_WAIT_L(n) asm volatile("s_waitcnt lgkmcnt(" #n ")" ::: "memory")
; #define PG8_BAR __builtin_amdgcn_s_barrier()
; #define PG8_SCHED __builtin_amdgcn_sched_barrier(0)
;     __device__ __forceinline__ void operator()(const f32x4 (&acc)[2][2][4][2], const Unit& u, int wr, int wc, int fr, int fq, const bool reuse, PG8_LAS float* rscr, PG8_LAS const float* gains) const {
;     ...
;                 f32x4 rs4[2][4];
; #pragma unroll
;                 for (int ai = 0; ai < 2; ++ai)
; #pragma unroll
;                     for (int m = 0; m < 4; ++m) { const int r = u.pm * BM + ai * HALF + wr * 64 + m * 16 + fr; rs4[ai][m] = *(const f32x4*)(rs + (size_t)(row_base + r) * 16 + 4 * fq); }
;     ...
;             PG8_WAIT_V(8); PG8_WAIT_L(0); PG8_BAR; PG8_MMA(0, 0, At, B0); PG8_MMA(0, 1, At, B1); PG8_BAR; PG8_SCHED;
;             PG8_LDA(At, 0, 1); PG8_STAGE(PG8_SB(0, 0), b2, voffB); PG8_STAGE(PG8_SB(0, 1), b2 + hstepB, voffB); PG8_STAGE(PG8_SA(0, 0), a2, voffA);
;             PG8_WAIT_V(8); PG8_WAIT_L(0); PG8_BAR; PG8_MMA(1, 0, At, B0); PG8_MMA(1, 1, At, B1); PG8_BAR; PG8_SCHED;
.Lpkb_da:
	s_waitcnt lgkmcnt(0)
	s_barrier
	v_mfma_f32_16x16x32_f16 v[132:135], v[112:115], v[160:163], v[132:135]
	v_mfma_f32_16x16x32_f16 v[128:131], v[120:123], v[160:163], v[128:131]
	v_mfma_f32_16x16x32_f16 v[100:103], v[112:115], v[168:171], v[100:103]
	v_mfma_f32_16x16x32_f16 v[96:99], v[120:123], v[168:171], v[96:99]
	v_mfma_f32_16x16x32_f16 v[84:87], v[112:115], v[202:205], v[84:87]
	v_mfma_f32_16x16x32_f16 v[80:83], v[120:123], v[202:205], v[80:83]
	v_mfma_f32_16x16x32_f16 v[68:71], v[112:115], v[210:213], v[68:71]
	v_mfma_f32_16x16x32_f16 v[64:67], v[120:123], v[210:213], v[64:67]
	v_mfma_f32_16x16x32_f16 v[132:135], v[116:119], v[164:167], v[132:135]
	v_mfma_f32_16x16x32_f16 v[128:131], v[124:127], v[164:167], v[128:131]
	v_mfma_f32_16x16x32_f16 v[100:103], v[116:119], v[192:195], v[100:103]
	v_mfma_f32_16x16x32_f16 v[96:99], v[124:127], v[192:195], v[96:99]
	v_mfma_f32_16x16x32_f16 v[84:87], v[116:119], v[206:209], v[84:87]
	v_mfma_f32_16x16x32_f16 v[80:83], v[124:127], v[206:209], v[80:83]
	v_mfma_f32_16x16x32_f16 v[68:71], v[116:119], v[214:217], v[68:71]
	v_mfma_f32_16x16x32_f16 v[64:67], v[124:127], v[214:217], v[64:67]
	v_mfma_f32_16x16x32_f16 v[140:143], v[144:147], v[160:163], v[140:143]
	v_mfma_f32_16x16x32_f16 v[136:139], v[152:155], v[160:163], v[136:139]
	v_mfma_f32_16x16x32_f16 v[108:111], v[144:147], v[168:171], v[108:111]
	v_mfma_f32_16x16x32_f16 v[104:107], v[152:155], v[168:171], v[104:107]
	v_mfma_f32_16x16x32_f16 v[92:95], v[144:147], v[202:205], v[92:95]
	v_mfma_f32_16x16x32_f16 v[88:91], v[152:155], v[202:205], v[88:91]
	v_mfma_f32_16x16x32_f16 v[76:79], v[144:147], v[210:213], v[76:79]
	v_mfma_f32_16x16x32_f16 v[72:75], v[152:155], v[210:213], v[72:75]
	v_mfma_f32_16x16x32_f16 v[140:143], v[148:151], v[164:167], v[140:143]
	v_mfma_f32_16x16x32_f16 v[136:139], v[156:159], v[164:167], v[136:139]
	v_mfma_f32_16x16x32_f16 v[108:111], v[148:151], v[192:195], v[108:111]
	v_mfma_f32_16x16x32_f16 v[104:107], v[156:159], v[192:195], v[104:107]
	v_mfma_f32_16x16x32_f16 v[92:95], v[148:151], v[206:209], v[92:95]
	v_mfma_f32_16x16x32_f16 v[88:91], v[156:159], v[206:209], v[88:91]
	v_mfma_f32_16x16x32_f16 v[76:79], v[148:151], v[214:217], v[76:79]
	v_mfma_f32_16x16x32_f16 v[72:75], v[156:159], v[214:217], v[72:75]
	s_barrier
	s_add_i32 s57, s51, s28
	v_lshl_add_u64 v[218:219], s[22:23], 0, v[174:175]
	s_mov_b32 m0, s57
	ds_read_b128 v[160:163], v200 offset:16384
	ds_read_b128 v[164:167], v200 offset:17408
	ds_read_b128 v[168:171], v200 offset:18432
	ds_read_b128 v[192:195], v200 offset:19456
	ds_read_b128 v[202:205], v200 offset:20480
	ds_read_b128 v[206:209], v200 offset:21504
	ds_read_b128 v[210:213], v200 offset:22528
	ds_read_b128 v[214:217], v200 offset:23552
	global_load_lds_dwordx4 v[218:219], off
	s_add_i32 m0, s57, 0x2000
	s_add_u32 s58, s22, 0x10000
	v_lshl_add_u64 v[220:221], s[22:23], 0, v[178:179]
	s_addc_u32 s59, s23, 0
	s_add_i32 s57, s52, s28
	global_load_lds_dwordx4 v[220:221], off
	v_lshl_add_u64 v[222:223], s[58:59], 0, v[174:175]
	s_mov_b32 m0, s57
	v_lshl_add_u64 v[224:225], s[26:27], 0, v[176:177]
	global_load_lds_dwordx4 v[222:223], off
	s_add_i32 m0, s57, 0x2000
	v_lshl_add_u64 v[222:223], s[58:59], 0, v[178:179]
	global_load_lds_dwordx4 v[222:223], off
	s_mov_b32 m0, s29
	v_lshl_add_u64 v[222:223], s[26:27], 0, v[172:173]
	global_load_lds_dwordx4 v[222:223], off
	s_mov_b32 m0, s41
	s_nop 0
	global_load_lds_dwordx4 v[224:225], off
	s_cmp_eq_u32 s56, 10
	s_cbranch_scc0 .Lrs_n
	s_cmp_lg_u32 s54, s38
	s_cbranch_scc0 .Lrs_n
	s_bitset1_b32 s101, 17
	s_lshl_b32 s32, s54, 8
	s_add_i32 s32, s32, s45
	s_bfe_u32 vcc_lo, s29, 0x2000a
	s_and_b32 vcc_hi, vcc_lo, 1
	s_lshl_b32 vcc_hi, vcc_hi, 5
	s_lshr_b32 m0, vcc_lo, 1
	s_lshl_b32 m0, m0, 7
	s_add_i32 vcc_hi, vcc_hi, m0
	s_add_i32 s32, s32, vcc_hi
	v_or_b32_e32 v228, s32, v196
	v_add_u32_e32 v230, 16, v228
	v_lshlrev_b32_e32 v228, 6, v228
	v_lshlrev_b32_e32 v230, 6, v230
	v_mov_b32_e32 v229, 0
	v_mov_b32_e32 v231, 0
	v_lshl_add_u64 v[228:229], v[228:229], 0, v[182:183]
	v_lshl_add_u64 v[230:231], v[230:231], 0, v[182:183]
	s_lshl_b32 vcc_lo, vcc_lo, 11
	s_lshr_b32 vcc_hi, s29, 12
	s_lshl_b32 vcc_hi, vcc_hi, 13
	s_add_i32 vcc_lo, vcc_lo, vcc_hi
	s_add_i32 m0, vcc_lo, 0x22000
	s_nop 0
	global_load_lds_dwordx4 v[228:229], off
	s_add_i32 m0, m0, 0x400
	s_nop 0
	global_load_lds_dwordx4 v[230:231], off

; #define PG8_STAGE(bufoff, gbase, voff) do { _Pragma("unroll") for (int _i = 0; _i < 2; ++_i) \
;         __builtin_amdgcn_global_load_lds((const unsigned*)((const char*)(gbase) + (voff)[_i]), (PG8_LAS unsigned*)(lds + (bufoff) + ldsw + _i * 8192), 16, 0, 0); } while (0)
; #define PG8_LDA(dst, b, h) do { _Pragma("unroll") for (int m = 0; m < 4; ++m) _Pragma("unroll") for (int k = 0; k < 2; ++k) dst[m][k] = *(const PG8_LAS bf16x8*)(lds + PG8_SA(b, h) + aoff + m * 2048 + k * 1024); } while (0)
; #define PG8_LDB(dst, b, h) do { _Pragma("unroll") for (int n = 0; n < 2; ++n) _Pragma("unroll") for (int k = 0; k < 2; ++k) dst[n][k] = *(const PG8_LAS bf16x8*)(lds + PG8_SB(b, h) + boff + n * 2048 + k * 1024); } while (0)
; #define PG8_WAIT_V(n) asm volatile("s_waitcnt vmcnt(" #n ")" ::: "memory")
; #define PG8_WAIT_L(n) asm volatile("s_waitcnt lgkmcnt(" #n ")" ::: "memory")
; #define PG8_BAR __builtin_amdgcn_s_barrier()
; #define PG8_SCHED __builtin_amdgcn_sched_barrier(0)
;     ...
;             PG8_WAIT_V(8); PG8_WAIT_L(0); PG8_BAR; PG8_MMA(1, 0, At, B0); PG8_MMA(1, 1, At, B1); PG8_BAR; PG8_SCHED;
;             PG8_LDB(B0, 1, 0); PG8_LDB(B1, 1, 1); PG8_SCHED; PG8_LDA(At, 1, 0); PG8_STAGE(PG8_SA(0, 1), a2 + hstep, voffA);
;             PG8_WAIT_V(8); PG8_WAIT_L(0); PG8_BAR; PG8_MMA(0, 0, At, B0); PG8_MMA(0, 1, At, B1); PG8_BAR; PG8_SCHED;
.Lpkb_db:
	s_waitcnt lgkmcnt(0)
	s_barrier
	v_mfma_f32_16x16x32_f16 v[52:55], v[112:115], v[160:163], v[52:55]
	v_mfma_f32_16x16x32_f16 v[48:51], v[120:123], v[160:163], v[48:51]
	v_mfma_f32_16x16x32_f16 v[36:39], v[112:115], v[168:171], v[36:39]
	v_mfma_f32_16x16x32_f16 v[32:35], v[120:123], v[168:171], v[32:35]
	v_mfma_f32_16x16x32_f16 v[20:23], v[112:115], v[202:205], v[20:23]
	v_mfma_f32_16x16x32_f16 v[16:19], v[120:123], v[202:205], v[16:19]
	v_mfma_f32_16x16x32_f16 v[4:7], v[112:115], v[210:213], v[4:7]
	v_mfma_f32_16x16x32_f16 v[0:3], v[120:123], v[210:213], v[0:3]
	v_mfma_f32_16x16x32_f16 v[52:55], v[116:119], v[164:167], v[52:55]
	v_mfma_f32_16x16x32_f16 v[48:51], v[124:127], v[164:167], v[48:51]
	v_mfma_f32_16x16x32_f16 v[36:39], v[116:119], v[192:195], v[36:39]
	v_mfma_f32_16x16x32_f16 v[32:35], v[124:127], v[192:195], v[32:35]
	v_mfma_f32_16x16x32_f16 v[20:23], v[116:119], v[206:209], v[20:23]
	v_mfma_f32_16x16x32_f16 v[16:19], v[124:127], v[206:209], v[16:19]
	v_mfma_f32_16x16x32_f16 v[4:7], v[116:119], v[214:217], v[4:7]
	v_mfma_f32_16x16x32_f16 v[0:3], v[124:127], v[214:217], v[0:3]
	v_mfma_f32_16x16x32_f16 v[60:63], v[144:147], v[160:163], v[60:63]
	v_mfma_f32_16x16x32_f16 v[56:59], v[152:155], v[160:163], v[56:59]
	v_mfma_f32_16x16x32_f16 v[44:47], v[144:147], v[168:171], v[44:47]
	v_mfma_f32_16x16x32_f16 v[40:43], v[152:155], v[168:171], v[40:43]
	v_mfma_f32_16x16x32_f16 v[28:31], v[144:147], v[202:205], v[28:31]
	v_mfma_f32_16x16x32_f16 v[24:27], v[152:155], v[202:205], v[24:27]
	v_mfma_f32_16x16x32_f16 v[12:15], v[144:147], v[210:213], v[12:15]
	v_mfma_f32_16x16x32_f16 v[8:11], v[152:155], v[210:213], v[8:11]
	v_mfma_f32_16x16x32_f16 v[60:63], v[148:151], v[164:167], v[60:63]
	v_mfma_f32_16x16x32_f16 v[56:59], v[156:159], v[164:167], v[56:59]
	v_mfma_f32_16x16x32_f16 v[44:47], v[148:151], v[192:195], v[44:47]
	v_mfma_f32_16x16x32_f16 v[40:43], v[156:159], v[192:195], v[40:43]
	v_mfma_f32_16x16x32_f16 v[28:31], v[148:151], v[206:209], v[28:31]
	v_mfma_f32_16x16x32_f16 v[24:27], v[156:159], v[206:209], v[24:27]
	v_mfma_f32_16x16x32_f16 v[12:15], v[148:151], v[214:217], v[12:15]
	v_mfma_f32_16x16x32_f16 v[8:11], v[156:159], v[214:217], v[8:11]
	s_barrier
	s_add_i32 s57, 0, 0x18000
	s_add_i32 s58, 0, 0x1c000
	v_add_u32_e32 v124, s57, v197
	v_add_u32_e32 v156, s58, v197
	ds_read_b128 v[112:115], v124
	ds_read_b128 v[116:119], v124 offset:1024
	ds_read_b128 v[120:123], v124 offset:2048
	ds_read_b128 v[124:127], v124 offset:3072
	ds_read_b128 v[144:147], v156
	ds_read_b128 v[148:151], v156 offset:1024
	ds_read_b128 v[152:155], v156 offset:2048
	ds_read_b128 v[156:159], v156 offset:3072
	s_add_u32 s26, s26, 0x40000
	s_addc_u32 s27, s27, 0
	s_mov_b32 m0, s42
	v_lshl_add_u64 v[226:227], s[26:27], 0, v[172:173]
	ds_read_b128 v[160:163], v200 offset:32768
	ds_read_b128 v[164:167], v200 offset:33792
	ds_read_b128 v[168:171], v200 offset:34816
	ds_read_b128 v[192:195], v200 offset:35840
	ds_read_b128 v[202:205], v200 offset:36864
	ds_read_b128 v[206:209], v200 offset:37888
	ds_read_b128 v[210:213], v200 offset:38912
	ds_read_b128 v[214:217], v200 offset:39936
	global_load_lds_dwordx4 v[226:227], off
	s_mov_b32 m0, s43
	v_lshl_add_u64 v[226:227], s[26:27], 0, v[176:177]
	global_load_lds_dwordx4 v[226:227], off
	s_bfe_u32 vcc_lo, s101, 0x20010
	s_cmp_eq_u32 vcc_lo, 0
	s_cbranch_scc1 .Lpkb_w8c
	s_cmp_eq_u32 vcc_lo, 1
	s_cbranch_scc1 .Lpkb_w9c
	s_cmp_eq_u32 vcc_lo, 2
	s_cbranch_scc1 .Lpkb_w10c
	s_waitcnt vmcnt(11)
	s_branch .Lpkb_dc

; #define PG8_STAGE(bufoff, gbase, voff) do { _Pragma("unroll") for (int _i = 0; _i < 2; ++_i) \
;         __builtin_amdgcn_global_load_lds((const unsigned*)((const char*)(gbase) + (voff)[_i]), (PG8_LAS unsigned*)(lds + (bufoff) + ldsw + _i * 8192), 16, 0, 0); } while (0)
; #define PG8_LDA(dst, b, h) do { _Pragma("unroll") for (int m = 0; m < 4; ++m) _Pragma("unroll") for (int k = 0; k < 2; ++k) dst[m][k] = *(const PG8_LAS bf16x8*)(lds + PG8_SA(b, h) + aoff + m * 2048 + k * 1024); } while (0)
; #define PG8_WAIT_V(n) asm volatile("s_waitcnt vmcnt(" #n ")" ::: "memory")
; #define PG8_WAIT_L(n) asm volatile("s_waitcnt lgkmcnt(" #n ")" ::: "memory")
; #define PG8_BAR __builtin_amdgcn_s_barrier()
; #define PG8_SCHED __builtin_amdgcn_sched_barrier(0)
;     ...
;             PG8_WAIT_V(8); PG8_WAIT_L(0); PG8_BAR; PG8_MMA(0, 0, At, B0); PG8_MMA(0, 1, At, B1); PG8_BAR; PG8_SCHED;
;             PG8_LDA(At, 1, 1); PG8_STAGE(PG8_SB(1, 0), b3, voffB); PG8_STAGE(PG8_SB(1, 1), b3 + hstepB, voffB); PG8_STAGE(PG8_SA(1, 0), a3, voffA);
;             PG8_WAIT_V(8); PG8_WAIT_L(0); PG8_BAR; PG8_MMA(1, 0, At, B0); PG8_MMA(1, 1, At, B1); PG8_BAR; PG8_SCHED;
.Lpkb_dc:
	s_waitcnt lgkmcnt(0)
	s_barrier
	v_mfma_f32_16x16x32_f16 v[132:135], v[112:115], v[160:163], v[132:135]
	v_mfma_f32_16x16x32_f16 v[128:131], v[120:123], v[160:163], v[128:131]
	v_mfma_f32_16x16x32_f16 v[100:103], v[112:115], v[168:171], v[100:103]
	v_mfma_f32_16x16x32_f16 v[96:99], v[120:123], v[168:171], v[96:99]
	v_mfma_f32_16x16x32_f16 v[84:87], v[112:115], v[202:205], v[84:87]
	v_mfma_f32_16x16x32_f16 v[80:83], v[120:123], v[202:205], v[80:83]
	v_mfma_f32_16x16x32_f16 v[68:71], v[112:115], v[210:213], v[68:71]
	v_mfma_f32_16x16x32_f16 v[64:67], v[120:123], v[210:213], v[64:67]
	v_mfma_f32_16x16x32_f16 v[132:135], v[116:119], v[164:167], v[132:135]
	v_mfma_f32_16x16x32_f16 v[128:131], v[124:127], v[164:167], v[128:131]
	v_mfma_f32_16x16x32_f16 v[100:103], v[116:119], v[192:195], v[100:103]
	v_mfma_f32_16x16x32_f16 v[96:99], v[124:127], v[192:195], v[96:99]
	v_mfma_f32_16x16x32_f16 v[84:87], v[116:119], v[206:209], v[84:87]
	v_mfma_f32_16x16x32_f16 v[80:83], v[124:127], v[206:209], v[80:83]
	v_mfma_f32_16x16x32_f16 v[68:71], v[116:119], v[214:217], v[68:71]
	v_mfma_f32_16x16x32_f16 v[64:67], v[124:127], v[214:217], v[64:67]
	v_mfma_f32_16x16x32_f16 v[140:143], v[144:147], v[160:163], v[140:143]
	v_mfma_f32_16x16x32_f16 v[136:139], v[152:155], v[160:163], v[136:139]
	v_mfma_f32_16x16x32_f16 v[108:111], v[144:147], v[168:171], v[108:111]
	v_mfma_f32_16x16x32_f16 v[104:107], v[152:155], v[168:171], v[104:107]
	v_mfma_f32_16x16x32_f16 v[92:95], v[144:147], v[202:205], v[92:95]
	v_mfma_f32_16x16x32_f16 v[88:91], v[152:155], v[202:205], v[88:91]
	v_mfma_f32_16x16x32_f16 v[76:79], v[144:147], v[210:213], v[76:79]
	v_mfma_f32_16x16x32_f16 v[72:75], v[152:155], v[210:213], v[72:75]
	v_mfma_f32_16x16x32_f16 v[140:143], v[148:151], v[164:167], v[140:143]
	v_mfma_f32_16x16x32_f16 v[136:139], v[156:159], v[164:167], v[136:139]
	v_mfma_f32_16x16x32_f16 v[108:111], v[148:151], v[192:195], v[108:111]
	v_mfma_f32_16x16x32_f16 v[104:107], v[156:159], v[192:195], v[104:107]
	v_mfma_f32_16x16x32_f16 v[92:95], v[148:151], v[206:209], v[92:95]
	v_mfma_f32_16x16x32_f16 v[88:91], v[156:159], v[206:209], v[88:91]
	v_mfma_f32_16x16x32_f16 v[76:79], v[148:151], v[214:217], v[76:79]
	v_mfma_f32_16x16x32_f16 v[72:75], v[156:159], v[214:217], v[72:75]
	s_barrier
	s_add_i32 s26, s57, s28
	v_lshl_add_u64 v[218:219], v[218:219], 0, s[10:11]
	s_mov_b32 m0, s26
	ds_read_b128 v[160:163], v200 offset:49152
	ds_read_b128 v[164:167], v200 offset:50176
	ds_read_b128 v[168:171], v200 offset:51200
	ds_read_b128 v[192:195], v200 offset:52224
	ds_read_b128 v[202:205], v200 offset:53248
	ds_read_b128 v[206:209], v200 offset:54272
	ds_read_b128 v[210:213], v200 offset:55296
	ds_read_b128 v[214:217], v200 offset:56320
	global_load_lds_dwordx4 v[218:219], off
	s_add_i32 m0, s26, 0x2000
	s_add_u32 s22, s22, 0x10080
	v_lshl_add_u64 v[218:219], v[220:221], 0, s[10:11]
	s_addc_u32 s23, s23, 0
	s_add_i32 s26, s58, s28
	global_load_lds_dwordx4 v[218:219], off
	s_mov_b32 m0, s26
	v_lshl_add_u64 v[218:219], s[22:23], 0, v[174:175]
	global_load_lds_dwordx4 v[218:219], off
	s_add_i32 m0, s26, 0x2000
	v_lshl_add_u64 v[218:219], s[22:23], 0, v[178:179]
	global_load_lds_dwordx4 v[218:219], off
	s_mov_b32 m0, s48
	v_lshl_add_u64 v[218:219], v[222:223], 0, s[10:11]
	global_load_lds_dwordx4 v[218:219], off
	s_mov_b32 m0, s49
	v_lshl_add_u64 v[218:219], v[224:225], 0, s[10:11]
	global_load_lds_dwordx4 v[218:219], off
	s_bitcmp1_b32 s101, 17
	s_cbranch_scc0 .Lpkb_w8e
	s_waitcnt vmcnt(10)
	s_branch .Lpkb_de

; #define PG8_STAGE(bufoff, gbase, voff) do { _Pragma("unroll") for (int _i = 0; _i < 2; ++_i) \
;         __builtin_amdgcn_global_load_lds((const unsigned*)((const char*)(gbase) + (voff)[_i]), (PG8_LAS unsigned*)(lds + (bufoff) + ldsw + _i * 8192), 16, 0, 0); } while (0)
; #define PG8_LDA(dst, b, h) do { _Pragma("unroll") for (int m = 0; m < 4; ++m) _Pragma("unroll") for (int k = 0; k < 2; ++k) dst[m][k] = *(const PG8_LAS bf16x8*)(lds + PG8_SA(b, h) + aoff + m * 2048 + k * 1024); } while (0)
; #define PG8_LDB(dst, b, h) do { _Pragma("unroll") for (int n = 0; n < 2; ++n) _Pragma("unroll") for (int k = 0; k < 2; ++k) dst[n][k] = *(const PG8_LAS bf16x8*)(lds + PG8_SB(b, h) + boff + n * 2048 + k * 1024); } while (0)
; #define PG8_WAIT_V(n) asm volatile("s_waitcnt vmcnt(" #n ")" ::: "memory")
; #define PG8_WAIT_L(n) asm volatile("s_waitcnt lgkmcnt(" #n ")" ::: "memory")
; #define PG8_BAR __builtin_amdgcn_s_barrier()
; #define PG8_SCHED __builtin_amdgcn_sched_barrier(0)
;     ...
;         for (int t = 0; t < nt; t += 2) {
;             const bool last = (t == nt - 2);
;             const char* a1 = cA + (size_t)(t + 1) * kstep;
;             const char* a2 = last ? nA : cA + (size_t)(t + 2) * kstep; const char* b2 = last ? nB : cB + (size_t)(t + 2) * kstep;
;             const char* a3 = a2 + kstep; const char* b3 = b2 + kstep;
;             PG8_LDB(B0, 0, 0); PG8_LDB(B1, 0, 1); PG8_SCHED; PG8_LDA(At, 0, 0); PG8_STAGE(PG8_SA(1, 1), a1 + hstep, voffA);
;             PG8_WAIT_V(8); PG8_WAIT_L(0); PG8_BAR; PG8_MMA(0, 0, At, B0); PG8_MMA(0, 1, At, B1); PG8_BAR; PG8_SCHED;
;             PG8_LDA(At, 0, 1); PG8_STAGE(PG8_SB(0, 0), b2, voffB); PG8_STAGE(PG8_SB(0, 1), b2 + hstepB, voffB); PG8_STAGE(PG8_SA(0, 0), a2, voffA);
.LBB0_732:
	v_add_u32_e32 v158, s37, v152
	v_add_u32_e32 v174, s38, v152
	ds_read_b128 v[128:131], v158
	ds_read_b128 v[148:151], v158 offset:1024
	ds_read_b128 v[154:157], v158 offset:2048
	ds_read_b128 v[158:161], v158 offset:3072
	ds_read_b128 v[162:165], v174
	ds_read_b128 v[166:169], v174 offset:1024
	ds_read_b128 v[170:173], v174 offset:2048
	ds_read_b128 v[174:177], v174 offset:3072
	s_add_u32 s20, s22, 0xfffc0080
	s_addc_u32 s21, s23, -1
	s_cmp_eq_u32 s53, 12
	s_cselect_b32 s25, s13, s21
	s_cselect_b32 s24, s49, s20
	s_cselect_b32 s21, s11, s52
	s_cselect_b32 s20, s50, s51
	v_lshl_add_u64 v[210:211], s[22:23], 0, v[140:141]
	s_add_i32 m0, s19, 0xc000
	ds_read_b128 v[178:181], v153
	ds_read_b128 v[182:185], v153 offset:1024
	ds_read_b128 v[186:189], v153 offset:2048
	ds_read_b128 v[190:193], v153 offset:3072
	ds_read_b128 v[194:197], v153 offset:4096
	ds_read_b128 v[198:201], v153 offset:5120
	ds_read_b128 v[202:205], v153 offset:6144
	ds_read_b128 v[206:209], v153 offset:7168
	global_load_lds_dwordx4 v[210:211], off
	s_add_i32 m0, s19, 0xe000
	v_lshl_add_u64 v[210:211], s[22:23], 0, v[142:143]
	global_load_lds_dwordx4 v[210:211], off
	s_waitcnt vmcnt(8)
	s_waitcnt lgkmcnt(0)
	s_barrier
	v_mfma_f32_16x16x32_bf16 v[112:115], v[128:131], v[178:181], v[112:115]
	v_mfma_f32_16x16x32_bf16 v[116:119], v[154:157], v[178:181], v[116:119]
	v_mfma_f32_16x16x32_bf16 v[108:111], v[128:131], v[186:189], v[108:111]
	v_mfma_f32_16x16x32_bf16 v[104:107], v[154:157], v[186:189], v[104:107]
	v_mfma_f32_16x16x32_bf16 v[92:95], v[128:131], v[194:197], v[92:95]
	v_mfma_f32_16x16x32_bf16 v[88:91], v[154:157], v[194:197], v[88:91]
	v_mfma_f32_16x16x32_bf16 v[76:79], v[128:131], v[202:205], v[76:79]
	v_mfma_f32_16x16x32_bf16 v[72:75], v[154:157], v[202:205], v[72:75]
	v_mfma_f32_16x16x32_bf16 v[112:115], v[148:151], v[182:185], v[112:115]
	v_mfma_f32_16x16x32_bf16 v[116:119], v[158:161], v[182:185], v[116:119]
	v_mfma_f32_16x16x32_bf16 v[108:111], v[148:151], v[190:193], v[108:111]
	v_mfma_f32_16x16x32_bf16 v[104:107], v[158:161], v[190:193], v[104:107]
	v_mfma_f32_16x16x32_bf16 v[92:95], v[148:151], v[198:201], v[92:95]
	v_mfma_f32_16x16x32_bf16 v[88:91], v[158:161], v[198:201], v[88:91]
	v_mfma_f32_16x16x32_bf16 v[76:79], v[148:151], v[206:209], v[76:79]
	v_mfma_f32_16x16x32_bf16 v[72:75], v[158:161], v[206:209], v[72:75]
	v_mfma_f32_16x16x32_bf16 v[120:123], v[162:165], v[178:181], v[120:123]
	v_mfma_f32_16x16x32_bf16 v[124:127], v[170:173], v[178:181], v[124:127]
	v_mfma_f32_16x16x32_bf16 v[100:103], v[162:165], v[186:189], v[100:103]
	v_mfma_f32_16x16x32_bf16 v[96:99], v[170:173], v[186:189], v[96:99]
	v_mfma_f32_16x16x32_bf16 v[84:87], v[162:165], v[194:197], v[84:87]
	v_mfma_f32_16x16x32_bf16 v[80:83], v[170:173], v[194:197], v[80:83]
	v_mfma_f32_16x16x32_bf16 v[68:71], v[162:165], v[202:205], v[68:71]
	v_mfma_f32_16x16x32_bf16 v[64:67], v[170:173], v[202:205], v[64:67]
	v_mfma_f32_16x16x32_bf16 v[120:123], v[166:169], v[182:185], v[120:123]
	v_mfma_f32_16x16x32_bf16 v[124:127], v[174:177], v[182:185], v[124:127]
	v_mfma_f32_16x16x32_bf16 v[100:103], v[166:169], v[190:193], v[100:103]
	v_mfma_f32_16x16x32_bf16 v[96:99], v[174:177], v[190:193], v[96:99]
	v_mfma_f32_16x16x32_bf16 v[84:87], v[166:169], v[198:201], v[84:87]
	v_mfma_f32_16x16x32_bf16 v[80:83], v[174:177], v[198:201], v[80:83]
	v_mfma_f32_16x16x32_bf16 v[68:71], v[166:169], v[206:209], v[68:71]
	v_mfma_f32_16x16x32_bf16 v[64:67], v[174:177], v[206:209], v[64:67]
	s_barrier
	s_add_i32 s54, s37, s26
	v_lshl_add_u64 v[210:211], s[20:21], 0, v[134:135]
	s_mov_b32 m0, s54
	ds_read_b128 v[178:181], v153 offset:16384
	ds_read_b128 v[182:185], v153 offset:17408
	ds_read_b128 v[186:189], v153 offset:18432
	ds_read_b128 v[190:193], v153 offset:19456
	ds_read_b128 v[194:197], v153 offset:20480
	ds_read_b128 v[198:201], v153 offset:21504
	ds_read_b128 v[202:205], v153 offset:22528
	ds_read_b128 v[206:209], v153 offset:23552
	global_load_lds_dwordx4 v[210:211], off
	s_add_i32 m0, s54, 0x2000
	s_add_u32 s54, s20, 0x40000
	v_lshl_add_u64 v[212:213], s[20:21], 0, v[132:133]
	s_addc_u32 s55, s21, 0
	s_add_i32 s56, s38, s26
	global_load_lds_dwordx4 v[212:213], off
	v_lshl_add_u64 v[214:215], s[54:55], 0, v[134:135]
	s_mov_b32 m0, s56
	v_lshl_add_u64 v[216:217], s[24:25], 0, v[132:133]
	global_load_lds_dwordx4 v[214:215], off
	s_add_i32 m0, s56, 0x2000
	v_lshl_add_u64 v[214:215], s[54:55], 0, v[132:133]
	global_load_lds_dwordx4 v[214:215], off
	s_mov_b32 m0, s19
	v_lshl_add_u64 v[214:215], s[24:25], 0, v[134:135]
	global_load_lds_dwordx4 v[214:215], off
	s_mov_b32 m0, s27
	s_nop 0
	global_load_lds_dwordx4 v[216:217], off
	s_waitcnt vmcnt(8)
	s_waitcnt lgkmcnt(0)
	s_barrier
; #define PG8_STAGE(bufoff, gbase, voff) do { _Pragma("unroll") for (int _i = 0; _i < 2; ++_i) \
;         __builtin_amdgcn_global_load_lds((const unsigned*)((const char*)(gbase) + (voff)[_i]), (PG8_LAS unsigned*)(lds + (bufoff) + ldsw + _i * 8192), 16, 0, 0); } while (0)
; #define PG8_LDA(dst, b, h) do { _Pragma("unroll") for (int m = 0; m < 4; ++m) _Pragma("unroll") for (int k = 0; k < 2; ++k) dst[m][k] = *(const PG8_LAS bf16x8*)(lds + PG8_SA(b, h) + aoff + m * 2048 + k * 1024); } while (0)
; #define PG8_LDB(dst, b, h) do { _Pragma("unroll") for (int n = 0; n < 2; ++n) _Pragma("unroll") for (int k = 0; k < 2; ++k) dst[n][k] = *(const PG8_LAS bf16x8*)(lds + PG8_SB(b, h) + boff + n * 2048 + k * 1024); } while (0)
; #define PG8_WAIT_V(n) asm volatile("s_waitcnt vmcnt(" #n ")" ::: "memory")
; #define PG8_WAIT_L(n) asm volatile("s_waitcnt lgkmcnt(" #n ")" ::: "memory")
; #define PG8_BAR __builtin_amdgcn_s_barrier()
; #define PG8_SCHED __builtin_amdgcn_sched_barrier(0)
;     ...
;             PG8_WAIT_V(8); PG8_WAIT_L(0); PG8_BAR; PG8_MMA(1, 0, At, B0); PG8_MMA(1, 1, At, B1); PG8_BAR; PG8_SCHED;
;             PG8_LDB(B0, 1, 0); PG8_LDB(B1, 1, 1); PG8_SCHED; PG8_LDA(At, 1, 0); PG8_STAGE(PG8_SA(0, 1), a2 + hstep, voffA);
;             PG8_WAIT_V(8); PG8_WAIT_L(0); PG8_BAR; PG8_MMA(0, 0, At, B0); PG8_MMA(0, 1, At, B1); PG8_BAR; PG8_SCHED;
	v_mfma_f32_16x16x32_bf16 v[60:63], v[128:131], v[178:181], v[60:63]
	v_mfma_f32_16x16x32_bf16 v[56:59], v[154:157], v[178:181], v[56:59]
	v_mfma_f32_16x16x32_bf16 v[44:47], v[128:131], v[186:189], v[44:47]
	v_mfma_f32_16x16x32_bf16 v[40:43], v[154:157], v[186:189], v[40:43]
	v_mfma_f32_16x16x32_bf16 v[28:31], v[128:131], v[194:197], v[28:31]
	v_mfma_f32_16x16x32_bf16 v[24:27], v[154:157], v[194:197], v[24:27]
	v_mfma_f32_16x16x32_bf16 v[12:15], v[128:131], v[202:205], v[12:15]
	v_mfma_f32_16x16x32_bf16 v[8:11], v[154:157], v[202:205], v[8:11]
	v_mfma_f32_16x16x32_bf16 v[60:63], v[148:151], v[182:185], v[60:63]
	v_mfma_f32_16x16x32_bf16 v[56:59], v[158:161], v[182:185], v[56:59]
	v_mfma_f32_16x16x32_bf16 v[44:47], v[148:151], v[190:193], v[44:47]
	v_mfma_f32_16x16x32_bf16 v[40:43], v[158:161], v[190:193], v[40:43]
	v_mfma_f32_16x16x32_bf16 v[28:31], v[148:151], v[198:201], v[28:31]
	v_mfma_f32_16x16x32_bf16 v[24:27], v[158:161], v[198:201], v[24:27]
	v_mfma_f32_16x16x32_bf16 v[12:15], v[148:151], v[206:209], v[12:15]
	v_mfma_f32_16x16x32_bf16 v[8:11], v[158:161], v[206:209], v[8:11]
	v_mfma_f32_16x16x32_bf16 v[52:55], v[162:165], v[178:181], v[52:55]
	v_mfma_f32_16x16x32_bf16 v[48:51], v[170:173], v[178:181], v[48:51]
	v_mfma_f32_16x16x32_bf16 v[36:39], v[162:165], v[186:189], v[36:39]
	v_mfma_f32_16x16x32_bf16 v[32:35], v[170:173], v[186:189], v[32:35]
	v_mfma_f32_16x16x32_bf16 v[20:23], v[162:165], v[194:197], v[20:23]
	v_mfma_f32_16x16x32_bf16 v[16:19], v[170:173], v[194:197], v[16:19]
	v_mfma_f32_16x16x32_bf16 v[0:3], v[162:165], v[202:205], v[0:3]
	v_mfma_f32_16x16x32_bf16 v[4:7], v[170:173], v[202:205], v[4:7]
	v_mfma_f32_16x16x32_bf16 v[52:55], v[166:169], v[182:185], v[52:55]
	v_mfma_f32_16x16x32_bf16 v[48:51], v[174:177], v[182:185], v[48:51]
	v_mfma_f32_16x16x32_bf16 v[36:39], v[166:169], v[190:193], v[36:39]
	v_mfma_f32_16x16x32_bf16 v[32:35], v[174:177], v[190:193], v[32:35]
	v_mfma_f32_16x16x32_bf16 v[20:23], v[166:169], v[198:201], v[20:23]
	v_mfma_f32_16x16x32_bf16 v[16:19], v[174:177], v[198:201], v[16:19]
	v_mfma_f32_16x16x32_bf16 v[0:3], v[166:169], v[206:209], v[0:3]
	v_mfma_f32_16x16x32_bf16 v[4:7], v[174:177], v[206:209], v[4:7]
	s_barrier
	s_add_i32 s54, 0, 0x18000
	s_add_i32 s55, 0, 0x1c000
	v_add_u32_e32 v158, s54, v152
	v_add_u32_e32 v174, s55, v152
	ds_read_b128 v[128:131], v158
	ds_read_b128 v[148:151], v158 offset:1024
	ds_read_b128 v[154:157], v158 offset:2048
	ds_read_b128 v[158:161], v158 offset:3072
	ds_read_b128 v[162:165], v174
	ds_read_b128 v[166:169], v174 offset:1024
	ds_read_b128 v[170:173], v174 offset:2048
	ds_read_b128 v[174:177], v174 offset:3072
	s_add_u32 s24, s24, 0x40000
	s_addc_u32 s25, s25, 0
	s_mov_b32 m0, s28
	v_lshl_add_u64 v[218:219], s[24:25], 0, v[134:135]
	ds_read_b128 v[178:181], v153 offset:32768
	ds_read_b128 v[182:185], v153 offset:33792
	ds_read_b128 v[186:189], v153 offset:34816
	ds_read_b128 v[190:193], v153 offset:35840
	ds_read_b128 v[194:197], v153 offset:36864
	ds_read_b128 v[198:201], v153 offset:37888
	ds_read_b128 v[202:205], v153 offset:38912
	ds_read_b128 v[206:209], v153 offset:39936
	global_load_lds_dwordx4 v[218:219], off
	s_mov_b32 m0, s29
	v_lshl_add_u64 v[218:219], s[24:25], 0, v[132:133]
	global_load_lds_dwordx4 v[218:219], off
	s_waitcnt vmcnt(8)
	s_waitcnt lgkmcnt(0)
	s_barrier
	v_mfma_f32_16x16x32_bf16 v[112:115], v[128:131], v[178:181], v[112:115]
	v_mfma_f32_16x16x32_bf16 v[116:119], v[154:157], v[178:181], v[116:119]
	v_mfma_f32_16x16x32_bf16 v[108:111], v[128:131], v[186:189], v[108:111]
	v_mfma_f32_16x16x32_bf16 v[104:107], v[154:157], v[186:189], v[104:107]
	v_mfma_f32_16x16x32_bf16 v[92:95], v[128:131], v[194:197], v[92:95]
	v_mfma_f32_16x16x32_bf16 v[88:91], v[154:157], v[194:197], v[88:91]
	v_mfma_f32_16x16x32_bf16 v[76:79], v[128:131], v[202:205], v[76:79]
	v_mfma_f32_16x16x32_bf16 v[72:75], v[154:157], v[202:205], v[72:75]
	v_mfma_f32_16x16x32_bf16 v[112:115], v[148:151], v[182:185], v[112:115]
	v_mfma_f32_16x16x32_bf16 v[116:119], v[158:161], v[182:185], v[116:119]
	v_mfma_f32_16x16x32_bf16 v[108:111], v[148:151], v[190:193], v[108:111]
	v_mfma_f32_16x16x32_bf16 v[104:107], v[158:161], v[190:193], v[104:107]
	v_mfma_f32_16x16x32_bf16 v[92:95], v[148:151], v[198:201], v[92:95]
	v_mfma_f32_16x16x32_bf16 v[88:91], v[158:161], v[198:201], v[88:91]
	v_mfma_f32_16x16x32_bf16 v[76:79], v[148:151], v[206:209], v[76:79]
	v_mfma_f32_16x16x32_bf16 v[72:75], v[158:161], v[206:209], v[72:75]
	v_mfma_f32_16x16x32_bf16 v[120:123], v[162:165], v[178:181], v[120:123]
	v_mfma_f32_16x16x32_bf16 v[124:127], v[170:173], v[178:181], v[124:127]
	v_mfma_f32_16x16x32_bf16 v[100:103], v[162:165], v[186:189], v[100:103]
	v_mfma_f32_16x16x32_bf16 v[96:99], v[170:173], v[186:189], v[96:99]
	v_mfma_f32_16x16x32_bf16 v[84:87], v[162:165], v[194:197], v[84:87]
	v_mfma_f32_16x16x32_bf16 v[80:83], v[170:173], v[194:197], v[80:83]
	v_mfma_f32_16x16x32_bf16 v[68:71], v[162:165], v[202:205], v[68:71]
	v_mfma_f32_16x16x32_bf16 v[64:67], v[170:173], v[202:205], v[64:67]
	v_mfma_f32_16x16x32_bf16 v[120:123], v[166:169], v[182:185], v[120:123]
	v_mfma_f32_16x16x32_bf16 v[124:127], v[174:177], v[182:185], v[124:127]
	v_mfma_f32_16x16x32_bf16 v[100:103], v[166:169], v[190:193], v[100:103]
	v_mfma_f32_16x16x32_bf16 v[96:99], v[174:177], v[190:193], v[96:99]
	v_mfma_f32_16x16x32_bf16 v[84:87], v[166:169], v[198:201], v[84:87]
	v_mfma_f32_16x16x32_bf16 v[80:83], v[174:177], v[198:201], v[80:83]
	v_mfma_f32_16x16x32_bf16 v[68:71], v[166:169], v[206:209], v[68:71]
	v_mfma_f32_16x16x32_bf16 v[64:67], v[174:177], v[206:209], v[64:67]
	s_barrier
; #define PG8_STAGE(bufoff, gbase, voff) do { _Pragma("unroll") for (int _i = 0; _i < 2; ++_i) \
;         __builtin_amdgcn_global_load_lds((const unsigned*)((const char*)(gbase) + (voff)[_i]), (PG8_LAS unsigned*)(lds + (bufoff) + ldsw + _i * 8192), 16, 0, 0); } while (0)
; #define PG8_LDA(dst, b, h) do { _Pragma("unroll") for (int m = 0; m < 4; ++m) _Pragma("unroll") for (int k = 0; k < 2; ++k) dst[m][k] = *(const PG8_LAS bf16x8*)(lds + PG8_SA(b, h) + aoff + m * 2048 + k * 1024); } while (0)
; #define PG8_WAIT_V(n) asm volatile("s_waitcnt vmcnt(" #n ")" ::: "memory")
; #define PG8_WAIT_L(n) asm volatile("s_waitcnt lgkmcnt(" #n ")" ::: "memory")
; #define PG8_BAR __builtin_amdgcn_s_barrier()
; #define PG8_SCHED __builtin_amdgcn_sched_barrier(0)
;     ...
;             PG8_LDA(At, 1, 1); PG8_STAGE(PG8_SB(1, 0), b3, voffB); PG8_STAGE(PG8_SB(1, 1), b3 + hstepB, voffB); PG8_STAGE(PG8_SA(1, 0), a3, voffA);
;             PG8_WAIT_V(8); PG8_WAIT_L(0); PG8_BAR; PG8_MMA(1, 0, At, B0); PG8_MMA(1, 1, At, B1); PG8_BAR; PG8_SCHED;
;         }
	s_add_i32 s24, s54, s26
	v_lshl_add_u64 v[210:211], v[210:211], 0, s[6:7]
	s_mov_b32 m0, s24
	ds_read_b128 v[178:181], v153 offset:49152
	ds_read_b128 v[182:185], v153 offset:50176
	ds_read_b128 v[186:189], v153 offset:51200
	ds_read_b128 v[190:193], v153 offset:52224
	ds_read_b128 v[194:197], v153 offset:53248
	ds_read_b128 v[198:201], v153 offset:54272
	ds_read_b128 v[202:205], v153 offset:55296
	ds_read_b128 v[206:209], v153 offset:56320
	global_load_lds_dwordx4 v[210:211], off
	s_add_i32 m0, s24, 0x2000
	s_add_u32 s20, s20, 0x40080
	v_lshl_add_u64 v[210:211], v[212:213], 0, s[6:7]
	s_addc_u32 s21, s21, 0
	s_add_i32 s24, s55, s26
	global_load_lds_dwordx4 v[210:211], off
	s_mov_b32 m0, s24
	v_lshl_add_u64 v[210:211], s[20:21], 0, v[134:135]
	global_load_lds_dwordx4 v[210:211], off
	s_add_i32 m0, s24, 0x2000
	v_lshl_add_u64 v[210:211], s[20:21], 0, v[132:133]
	global_load_lds_dwordx4 v[210:211], off
	s_mov_b32 m0, s33
	v_lshl_add_u64 v[210:211], v[214:215], 0, s[6:7]
	global_load_lds_dwordx4 v[210:211], off
	s_mov_b32 m0, s34
	v_lshl_add_u64 v[210:211], v[216:217], 0, s[6:7]
	global_load_lds_dwordx4 v[210:211], off
	s_waitcnt vmcnt(8)
	s_waitcnt lgkmcnt(0)
	s_barrier
	v_mfma_f32_16x16x32_bf16 v[60:63], v[128:131], v[178:181], v[60:63]
	v_mfma_f32_16x16x32_bf16 v[56:59], v[154:157], v[178:181], v[56:59]
	v_mfma_f32_16x16x32_bf16 v[44:47], v[128:131], v[186:189], v[44:47]
	v_mfma_f32_16x16x32_bf16 v[40:43], v[154:157], v[186:189], v[40:43]
	v_mfma_f32_16x16x32_bf16 v[28:31], v[128:131], v[194:197], v[28:31]
	v_mfma_f32_16x16x32_bf16 v[24:27], v[154:157], v[194:197], v[24:27]
	v_mfma_f32_16x16x32_bf16 v[12:15], v[128:131], v[202:205], v[12:15]
	v_mfma_f32_16x16x32_bf16 v[8:11], v[154:157], v[202:205], v[8:11]
	v_mfma_f32_16x16x32_bf16 v[60:63], v[148:151], v[182:185], v[60:63]
	v_mfma_f32_16x16x32_bf16 v[56:59], v[158:161], v[182:185], v[56:59]
	v_mfma_f32_16x16x32_bf16 v[44:47], v[148:151], v[190:193], v[44:47]
	v_mfma_f32_16x16x32_bf16 v[40:43], v[158:161], v[190:193], v[40:43]
	v_mfma_f32_16x16x32_bf16 v[28:31], v[148:151], v[198:201], v[28:31]
	v_mfma_f32_16x16x32_bf16 v[24:27], v[158:161], v[198:201], v[24:27]
	v_mfma_f32_16x16x32_bf16 v[12:15], v[148:151], v[206:209], v[12:15]
	v_mfma_f32_16x16x32_bf16 v[8:11], v[158:161], v[206:209], v[8:11]
	v_mfma_f32_16x16x32_bf16 v[52:55], v[162:165], v[178:181], v[52:55]
	v_mfma_f32_16x16x32_bf16 v[48:51], v[170:173], v[178:181], v[48:51]
	v_mfma_f32_16x16x32_bf16 v[36:39], v[162:165], v[186:189], v[36:39]
	v_mfma_f32_16x16x32_bf16 v[32:35], v[170:173], v[186:189], v[32:35]
	v_mfma_f32_16x16x32_bf16 v[20:23], v[162:165], v[194:197], v[20:23]
	v_mfma_f32_16x16x32_bf16 v[16:19], v[170:173], v[194:197], v[16:19]
	v_mfma_f32_16x16x32_bf16 v[0:3], v[162:165], v[202:205], v[0:3]
	v_mfma_f32_16x16x32_bf16 v[4:7], v[170:173], v[202:205], v[4:7]
	v_mfma_f32_16x16x32_bf16 v[52:55], v[166:169], v[182:185], v[52:55]
	v_mfma_f32_16x16x32_bf16 v[48:51], v[174:177], v[182:185], v[48:51]
	v_mfma_f32_16x16x32_bf16 v[36:39], v[166:169], v[190:193], v[36:39]
	v_mfma_f32_16x16x32_bf16 v[32:35], v[174:177], v[190:193], v[32:35]
	v_mfma_f32_16x16x32_bf16 v[20:23], v[166:169], v[198:201], v[20:23]
	v_mfma_f32_16x16x32_bf16 v[16:19], v[174:177], v[198:201], v[16:19]
	v_mfma_f32_16x16x32_bf16 v[0:3], v[166:169], v[206:209], v[0:3]
	v_mfma_f32_16x16x32_bf16 v[4:7], v[174:177], v[206:209], v[4:7]
	s_barrier
	s_add_i32 s53, s53, 2
	s_add_u32 s22, s22, 0x100
	s_addc_u32 s23, s23, 0
	s_add_u32 s51, s51, 0x100
	s_addc_u32 s52, s52, 0
	s_cmp_gt_u32 s53, 13
	s_cbranch_scc0 .LBB0_732
	s_and_b64 vcc, exec, s[8:9]
	s_cbranch_vccz .LBB0_735
	s_barrier
